# out/down GEMM residual epilogues: the 16 residual-row loads of a tile issued together (no store/atomic drain between row groups)
# speedup vs baseline: 1.0149x; 1.0083x over previous
.LBB0_1042:
	v_lshl_add_u32 v142, s56, 8, v146
	v_lshl_or_b32 v138, s58, 8, v148
	v_ashrrev_i32_e32 v143, 31, v142
	v_ashrrev_i32_e32 v139, 31, v138
	v_lshlrev_b64 v[140:141], 11, v[142:143]
	v_lshl_add_u64 v[150:151], s[42:43], 0, v[140:141]
	v_lshlrev_b64 v[138:139], 1, v[138:139]
	v_lshl_add_u64 v[154:155], v[150:151], 0, v[138:139]
	global_load_dwordx4 v[150:153], v[154:155], off
	global_load_dwordx4 v[160:163], v[154:155], off offset:256
	v_add_co_u32_e32 v230, vcc, 0x8000, v154
	s_nop 1
	v_addc_co_u32_e32 v231, vcc, 0, v155, vcc
	global_load_dwordx4 v[164:167], v[230:231], off
	global_load_dwordx4 v[168:171], v[230:231], off offset:256
	v_add_co_u32_e32 v230, vcc, 0x10000, v154
	s_nop 1
	v_addc_co_u32_e32 v231, vcc, 0, v155, vcc
	global_load_dwordx4 v[172:175], v[230:231], off
	global_load_dwordx4 v[176:179], v[230:231], off offset:256
	v_add_co_u32_e32 v230, vcc, 0x18000, v154
	s_nop 1
	v_addc_co_u32_e32 v231, vcc, 0, v155, vcc
	global_load_dwordx4 v[180:183], v[230:231], off
	global_load_dwordx4 v[184:187], v[230:231], off offset:256
	v_add_co_u32_e32 v230, vcc, 0x40000, v154
	s_nop 1
	v_addc_co_u32_e32 v231, vcc, 0, v155, vcc
	global_load_dwordx4 v[188:191], v[230:231], off
	global_load_dwordx4 v[206:209], v[230:231], off offset:256
	v_add_co_u32_e32 v230, vcc, 0x48000, v154
	s_nop 1
	v_addc_co_u32_e32 v231, vcc, 0, v155, vcc
	global_load_dwordx4 v[210:213], v[230:231], off
	global_load_dwordx4 v[214:217], v[230:231], off offset:256
	v_add_co_u32_e32 v230, vcc, 0x50000, v154
	s_nop 1
	v_addc_co_u32_e32 v231, vcc, 0, v155, vcc
	global_load_dwordx4 v[218:221], v[230:231], off
	global_load_dwordx4 v[222:225], v[230:231], off offset:256
	v_add_co_u32_e32 v230, vcc, 0x58000, v154
	s_nop 1
	v_addc_co_u32_e32 v231, vcc, 0, v155, vcc
	global_load_dwordx4 v[226:229], v[230:231], off
	global_load_dwordx4 v[230:233], v[230:231], off offset:256
	s_waitcnt vmcnt(0)
	v_lshlrev_b32_e32 v156, 16, v150
	v_and_b32_e32 v157, 0xffff0000, v150
	v_lshlrev_b32_e32 v150, 16, v151
	v_and_b32_e32 v151, 0xffff0000, v151
	v_lshlrev_b32_e32 v158, 16, v152
	v_and_b32_e32 v159, 0xffff0000, v152
	v_lshlrev_b32_e32 v152, 16, v153
	v_and_b32_e32 v153, 0xffff0000, v153
	v_pk_add_f32 v[126:127], v[126:127], v[150:151]
	v_pk_add_f32 v[124:125], v[124:125], v[156:157]
	v_pk_add_f32 v[150:151], v[122:123], v[152:153]
	v_pk_add_f32 v[122:123], v[120:121], v[158:159]
	v_mul_f32_e32 v120, v125, v125
	v_mul_f32_e32 v121, v127, v127
	v_fmac_f32_e32 v120, v124, v124
	v_fmac_f32_e32 v121, v126, v126
	v_add_f32_e32 v120, v120, v121
	v_mul_f32_e32 v121, v123, v123
	v_fmac_f32_e32 v121, v122, v122
	v_add_f32_e32 v120, v121, v120
	v_mul_f32_e32 v121, v151, v151
	v_fmac_f32_e32 v121, v150, v150
	v_add_f32_e32 v152, v121, v120
	v_cvt_pk_bf16_f32 v120, v124, v125
	v_lshl_add_u64 v[124:125], s[44:45], 0, v[140:141]
	v_cvt_pk_bf16_f32 v121, v126, v127
	v_cvt_pk_bf16_f32 v122, v122, v123
	v_cvt_pk_bf16_f32 v123, v150, v151
	v_lshl_add_u64 v[124:125], v[124:125], 0, v[138:139]
	global_store_dwordx4 v[124:125], v[120:123], off
	s_nop 1
	v_mov_b64_e32 v[120:121], v[160:161]
	v_mov_b64_e32 v[122:123], v[162:163]
	v_lshlrev_b32_e32 v126, 16, v120
	v_and_b32_e32 v127, 0xffff0000, v120
	v_lshlrev_b32_e32 v120, 16, v121
	v_and_b32_e32 v121, 0xffff0000, v121
	v_lshlrev_b32_e32 v150, 16, v122
	v_and_b32_e32 v151, 0xffff0000, v122
	v_lshlrev_b32_e32 v122, 16, v123
	v_and_b32_e32 v123, 0xffff0000, v123
	v_pk_add_f32 v[118:119], v[118:119], v[120:121]
	v_pk_add_f32 v[116:117], v[116:117], v[126:127]
	v_pk_add_f32 v[120:121], v[114:115], v[122:123]
	v_pk_add_f32 v[114:115], v[112:113], v[150:151]
	v_mul_f32_e32 v112, v117, v117
	v_mul_f32_e32 v113, v119, v119
	v_fmac_f32_e32 v112, v116, v116
	v_fmac_f32_e32 v113, v118, v118
	v_add_f32_e32 v112, v112, v113
	v_mul_f32_e32 v113, v115, v115
	v_fmac_f32_e32 v113, v114, v114
	v_add_f32_e32 v112, v113, v112
	v_mul_f32_e32 v113, v121, v121
	v_fmac_f32_e32 v113, v120, v120
	v_add_f32_e32 v112, v113, v112
	v_add_f32_e32 v122, v152, v112
	v_cvt_pk_bf16_f32 v112, v116, v117
	v_cvt_pk_bf16_f32 v113, v118, v119
	v_cvt_pk_bf16_f32 v114, v114, v115
	v_cvt_pk_bf16_f32 v115, v120, v121
	global_store_dwordx4 v[124:125], v[112:115], off offset:256
	s_nop 1
	v_mbcnt_hi_u32_b32 v112, -1, v234
	v_and_b32_e32 v114, 64, v112
	v_xor_b32_e32 v113, 16, v112
	v_add_u32_e32 v115, 64, v114
	v_cmp_lt_i32_e32 vcc, v113, v115
	s_nop 1
	v_cndmask_b32_e32 v113, v112, v113, vcc
	v_lshlrev_b32_e32 v114, 2, v113
	ds_bpermute_b32 v113, v114, v122
	s_waitcnt lgkmcnt(0)
	v_add_f32_e32 v116, v122, v113
	v_xor_b32_e32 v113, 32, v112
	v_cmp_lt_i32_e32 vcc, v113, v115
	s_nop 1
	v_cndmask_b32_e32 v112, v112, v113, vcc
	v_lshlrev_b32_e32 v115, 2, v112
	ds_bpermute_b32 v117, v115, v116
	v_lshl_add_u64 v[112:113], v[142:143], 2, s[30:31]
	s_and_saveexec_b64 s[56:57], s[38:39]
	s_cbranch_execz .LBB0_1044
	s_waitcnt lgkmcnt(0)
	v_add_f32_e32 v116, v116, v117
	global_atomic_add_f32 v[112:113], v116, off
.LBB0_1044:
	s_or_b64 exec, exec, s[56:57]
	v_or_b32_e32 v116, 16, v142
	s_waitcnt lgkmcnt(0)
	v_ashrrev_i32_e32 v117, 31, v116
	v_lshlrev_b64 v[120:121], 11, v[116:117]
	v_lshl_add_u64 v[116:117], s[42:43], 0, v[120:121]
	v_lshl_add_u64 v[122:123], v[116:117], 0, v[138:139]
	s_nop 1
	v_mov_b64_e32 v[116:117], v[164:165]
	v_mov_b64_e32 v[118:119], v[166:167]
	v_lshlrev_b32_e32 v124, 16, v116
	v_and_b32_e32 v125, 0xffff0000, v116
	v_lshlrev_b32_e32 v116, 16, v117
	v_and_b32_e32 v117, 0xffff0000, v117
	v_lshlrev_b32_e32 v126, 16, v118
	v_and_b32_e32 v127, 0xffff0000, v118
	v_lshlrev_b32_e32 v118, 16, v119
	v_and_b32_e32 v119, 0xffff0000, v119
	v_pk_add_f32 v[116:117], v[110:111], v[116:117]
	v_pk_add_f32 v[124:125], v[108:109], v[124:125]
	v_pk_add_f32 v[118:119], v[106:107], v[118:119]
	v_pk_add_f32 v[126:127], v[104:105], v[126:127]
	v_cvt_pk_bf16_f32 v104, v124, v125
	v_cvt_pk_bf16_f32 v105, v116, v117
	v_mul_f32_e32 v117, v117, v117
	v_cvt_pk_bf16_f32 v106, v126, v127
	v_cvt_pk_bf16_f32 v107, v118, v119
	s_nop 1
	v_mov_b64_e32 v[108:109], v[168:169]
	v_mov_b64_e32 v[110:111], v[170:171]
	v_mul_f32_e32 v122, v125, v125
	v_mul_f32_e32 v123, v127, v127
	v_fmac_f32_e32 v122, v124, v124
	v_fmac_f32_e32 v117, v116, v116
	v_mul_f32_e32 v119, v119, v119
	v_fmac_f32_e32 v123, v126, v126
	v_add_f32_e32 v116, v122, v117
	v_fmac_f32_e32 v119, v118, v118
	v_add_f32_e32 v116, v123, v116
	v_add_f32_e32 v122, v119, v116
	v_lshlrev_b32_e32 v116, 16, v108
	v_and_b32_e32 v117, 0xffff0000, v108
	v_lshlrev_b32_e32 v108, 16, v109
	v_and_b32_e32 v109, 0xffff0000, v109
	v_lshlrev_b32_e32 v118, 16, v110
	v_and_b32_e32 v119, 0xffff0000, v110
	v_lshlrev_b32_e32 v110, 16, v111
	v_and_b32_e32 v111, 0xffff0000, v111
	v_pk_add_f32 v[102:103], v[102:103], v[108:109]
	v_pk_add_f32 v[100:101], v[100:101], v[116:117]
	v_pk_add_f32 v[108:109], v[98:99], v[110:111]
	v_pk_add_f32 v[110:111], v[96:97], v[118:119]
	v_mul_f32_e32 v96, v101, v101
	v_mul_f32_e32 v97, v103, v103
	v_mul_f32_e32 v98, v111, v111
	v_fmac_f32_e32 v96, v100, v100
	v_fmac_f32_e32 v97, v102, v102
	v_mul_f32_e32 v99, v109, v109
	v_fmac_f32_e32 v98, v110, v110
	v_add_f32_e32 v96, v96, v97
	v_add_f32_e32 v96, v98, v96
	v_fmac_f32_e32 v99, v108, v108
	v_add_f32_e32 v96, v99, v96
	v_add_f32_e32 v99, v122, v96
	ds_bpermute_b32 v118, v114, v99
	v_lshl_add_u64 v[96:97], s[44:45], 0, v[120:121]
	v_lshl_add_u64 v[116:117], v[96:97], 0, v[138:139]
	global_store_dwordx4 v[116:117], v[104:107], off
	v_cvt_pk_bf16_f32 v98, v100, v101
	s_waitcnt lgkmcnt(0)
	v_add_f32_e32 v96, v99, v118
	ds_bpermute_b32 v97, v115, v96
	v_cvt_pk_bf16_f32 v99, v102, v103
	v_cvt_pk_bf16_f32 v100, v110, v111
	v_cvt_pk_bf16_f32 v101, v108, v109
	global_store_dwordx4 v[116:117], v[98:101], off offset:256
	s_and_saveexec_b64 s[56:57], s[38:39]
	s_cbranch_execz .LBB0_1046
	s_waitcnt lgkmcnt(0)
	v_add_f32_e32 v96, v96, v97
	global_atomic_add_f32 v[112:113], v96, off offset:64
.LBB0_1046:
	s_or_b64 exec, exec, s[56:57]
	v_or_b32_e32 v96, 32, v142
	s_waitcnt lgkmcnt(0)
	v_ashrrev_i32_e32 v97, 31, v96
	v_lshlrev_b64 v[100:101], 11, v[96:97]
	v_lshl_add_u64 v[96:97], s[42:43], 0, v[100:101]
	v_lshl_add_u64 v[102:103], v[96:97], 0, v[138:139]
	s_nop 1
	v_mov_b64_e32 v[96:97], v[172:173]
	v_mov_b64_e32 v[98:99], v[174:175]
	v_lshlrev_b32_e32 v104, 16, v96
	v_and_b32_e32 v105, 0xffff0000, v96
	v_lshlrev_b32_e32 v96, 16, v97
	v_and_b32_e32 v97, 0xffff0000, v97
	v_lshlrev_b32_e32 v106, 16, v98
	v_and_b32_e32 v107, 0xffff0000, v98
	v_lshlrev_b32_e32 v98, 16, v99
	v_and_b32_e32 v99, 0xffff0000, v99
	v_pk_add_f32 v[96:97], v[94:95], v[96:97]
	v_pk_add_f32 v[104:105], v[92:93], v[104:105]
	v_pk_add_f32 v[98:99], v[90:91], v[98:99]
	v_pk_add_f32 v[106:107], v[88:89], v[106:107]
	v_cvt_pk_bf16_f32 v88, v104, v105
	v_cvt_pk_bf16_f32 v89, v96, v97
	v_mul_f32_e32 v97, v97, v97
	v_cvt_pk_bf16_f32 v90, v106, v107
	v_cvt_pk_bf16_f32 v91, v98, v99
	s_nop 1
	v_mov_b64_e32 v[92:93], v[176:177]
	v_mov_b64_e32 v[94:95], v[178:179]
	v_mul_f32_e32 v102, v105, v105
	v_mul_f32_e32 v103, v107, v107
	v_fmac_f32_e32 v102, v104, v104
	v_fmac_f32_e32 v97, v96, v96
	v_mul_f32_e32 v99, v99, v99
	v_fmac_f32_e32 v103, v106, v106
	v_add_f32_e32 v96, v102, v97
	v_fmac_f32_e32 v99, v98, v98
	v_add_f32_e32 v96, v103, v96
	v_add_f32_e32 v102, v99, v96
	v_lshlrev_b32_e32 v96, 16, v92
	v_and_b32_e32 v97, 0xffff0000, v92
	v_lshlrev_b32_e32 v92, 16, v93
	v_and_b32_e32 v93, 0xffff0000, v93
	v_lshlrev_b32_e32 v98, 16, v94
	v_and_b32_e32 v99, 0xffff0000, v94
	v_lshlrev_b32_e32 v94, 16, v95
	v_and_b32_e32 v95, 0xffff0000, v95
	v_pk_add_f32 v[86:87], v[86:87], v[92:93]
	v_pk_add_f32 v[84:85], v[84:85], v[96:97]
	v_pk_add_f32 v[92:93], v[82:83], v[94:95]
	v_pk_add_f32 v[94:95], v[80:81], v[98:99]
	v_mul_f32_e32 v80, v85, v85
	v_mul_f32_e32 v81, v87, v87
	v_mul_f32_e32 v82, v95, v95
	v_fmac_f32_e32 v80, v84, v84
	v_fmac_f32_e32 v81, v86, v86
	v_mul_f32_e32 v83, v93, v93
	v_fmac_f32_e32 v82, v94, v94
	v_add_f32_e32 v80, v80, v81
	v_add_f32_e32 v80, v82, v80
	v_fmac_f32_e32 v83, v92, v92
	v_add_f32_e32 v80, v83, v80
	v_add_f32_e32 v83, v102, v80
	ds_bpermute_b32 v98, v114, v83
	v_lshl_add_u64 v[80:81], s[44:45], 0, v[100:101]
	v_lshl_add_u64 v[96:97], v[80:81], 0, v[138:139]
	global_store_dwordx4 v[96:97], v[88:91], off
	v_cvt_pk_bf16_f32 v82, v84, v85
	s_waitcnt lgkmcnt(0)
	v_add_f32_e32 v80, v83, v98
	ds_bpermute_b32 v81, v115, v80
	v_cvt_pk_bf16_f32 v83, v86, v87
	v_cvt_pk_bf16_f32 v84, v94, v95
	v_cvt_pk_bf16_f32 v85, v92, v93
	global_store_dwordx4 v[96:97], v[82:85], off offset:256
	s_and_saveexec_b64 s[56:57], s[38:39]
	s_cbranch_execz .LBB0_1048
	s_waitcnt lgkmcnt(0)
	v_add_f32_e32 v80, v80, v81
	global_atomic_add_f32 v[112:113], v80, off offset:128
.LBB0_1048:
	s_or_b64 exec, exec, s[56:57]
	v_or_b32_e32 v80, 48, v142
	s_waitcnt lgkmcnt(0)
	v_ashrrev_i32_e32 v81, 31, v80
	v_lshlrev_b64 v[84:85], 11, v[80:81]
	v_lshl_add_u64 v[80:81], s[42:43], 0, v[84:85]
	v_lshl_add_u64 v[86:87], v[80:81], 0, v[138:139]
	s_nop 1
	v_mov_b64_e32 v[80:81], v[180:181]
	v_mov_b64_e32 v[82:83], v[182:183]
	v_lshlrev_b32_e32 v88, 16, v80
	v_and_b32_e32 v89, 0xffff0000, v80
	v_lshlrev_b32_e32 v80, 16, v81
	v_and_b32_e32 v81, 0xffff0000, v81
	v_lshlrev_b32_e32 v90, 16, v82
	v_and_b32_e32 v91, 0xffff0000, v82
	v_lshlrev_b32_e32 v82, 16, v83
	v_and_b32_e32 v83, 0xffff0000, v83
	v_pk_add_f32 v[80:81], v[78:79], v[80:81]
	v_pk_add_f32 v[88:89], v[76:77], v[88:89]
	v_pk_add_f32 v[82:83], v[74:75], v[82:83]
	v_pk_add_f32 v[90:91], v[72:73], v[90:91]
	v_cvt_pk_bf16_f32 v72, v88, v89
	v_cvt_pk_bf16_f32 v73, v80, v81
	v_mul_f32_e32 v81, v81, v81
	v_cvt_pk_bf16_f32 v74, v90, v91
	v_cvt_pk_bf16_f32 v75, v82, v83
	s_nop 1
	v_mov_b64_e32 v[76:77], v[184:185]
	v_mov_b64_e32 v[78:79], v[186:187]
	v_mul_f32_e32 v86, v89, v89
	v_mul_f32_e32 v87, v91, v91
	v_fmac_f32_e32 v86, v88, v88
	v_fmac_f32_e32 v81, v80, v80
	v_mul_f32_e32 v83, v83, v83
	v_fmac_f32_e32 v87, v90, v90
	v_add_f32_e32 v80, v86, v81
	v_fmac_f32_e32 v83, v82, v82
	v_add_f32_e32 v80, v87, v80
	v_add_f32_e32 v86, v83, v80
	v_lshlrev_b32_e32 v80, 16, v76
	v_and_b32_e32 v81, 0xffff0000, v76
	v_lshlrev_b32_e32 v76, 16, v77
	v_and_b32_e32 v77, 0xffff0000, v77
	v_lshlrev_b32_e32 v82, 16, v78
	v_and_b32_e32 v83, 0xffff0000, v78
	v_lshlrev_b32_e32 v78, 16, v79
	v_and_b32_e32 v79, 0xffff0000, v79
	v_pk_add_f32 v[70:71], v[70:71], v[76:77]
	v_pk_add_f32 v[68:69], v[68:69], v[80:81]
	v_pk_add_f32 v[76:77], v[66:67], v[78:79]
	v_pk_add_f32 v[78:79], v[64:65], v[82:83]
	v_mul_f32_e32 v64, v69, v69
	v_mul_f32_e32 v65, v71, v71
	v_mul_f32_e32 v66, v79, v79
	v_fmac_f32_e32 v64, v68, v68
	v_fmac_f32_e32 v65, v70, v70
	v_mul_f32_e32 v67, v77, v77
	v_fmac_f32_e32 v66, v78, v78
	v_add_f32_e32 v64, v64, v65
	v_add_f32_e32 v64, v66, v64
	v_fmac_f32_e32 v67, v76, v76
	v_add_f32_e32 v64, v67, v64
	v_add_f32_e32 v67, v86, v64
	ds_bpermute_b32 v82, v114, v67
	v_lshl_add_u64 v[64:65], s[44:45], 0, v[84:85]
	v_lshl_add_u64 v[80:81], v[64:65], 0, v[138:139]
	global_store_dwordx4 v[80:81], v[72:75], off
	v_cvt_pk_bf16_f32 v66, v68, v69
	s_waitcnt lgkmcnt(0)
	v_add_f32_e32 v64, v67, v82
	ds_bpermute_b32 v65, v115, v64
	v_cvt_pk_bf16_f32 v67, v70, v71
	v_cvt_pk_bf16_f32 v68, v78, v79
	v_cvt_pk_bf16_f32 v69, v76, v77
	global_store_dwordx4 v[80:81], v[66:69], off offset:256
	s_and_saveexec_b64 s[56:57], s[38:39]
	s_cbranch_execz .LBB0_1050
	s_waitcnt lgkmcnt(0)
	v_add_f32_e32 v64, v64, v65
	global_atomic_add_f32 v[112:113], v64, off offset:192
.LBB0_1050:
	s_or_b64 exec, exec, s[56:57]
	s_mov_b64 s[10:11], 0x40000
	v_lshl_add_u64 v[68:69], v[140:141], 0, s[10:11]
	s_waitcnt lgkmcnt(0)
	v_lshl_add_u64 v[64:65], s[42:43], 0, v[68:69]
	v_lshl_add_u64 v[70:71], v[64:65], 0, v[138:139]
	s_nop 1
	v_mov_b64_e32 v[64:65], v[188:189]
	v_mov_b64_e32 v[66:67], v[190:191]
	v_lshlrev_b32_e32 v72, 16, v64
	v_and_b32_e32 v73, 0xffff0000, v64
	v_lshlrev_b32_e32 v64, 16, v65
	v_and_b32_e32 v65, 0xffff0000, v65
	v_lshlrev_b32_e32 v74, 16, v66
	v_and_b32_e32 v75, 0xffff0000, v66
	v_lshlrev_b32_e32 v66, 16, v67
	v_and_b32_e32 v67, 0xffff0000, v67
	v_pk_add_f32 v[64:65], v[62:63], v[64:65]
	v_pk_add_f32 v[72:73], v[60:61], v[72:73]
	v_pk_add_f32 v[66:67], v[58:59], v[66:67]
	v_pk_add_f32 v[74:75], v[56:57], v[74:75]
	v_cvt_pk_bf16_f32 v56, v72, v73
	v_cvt_pk_bf16_f32 v57, v64, v65
	v_mul_f32_e32 v65, v65, v65
	v_cvt_pk_bf16_f32 v58, v74, v75
	v_cvt_pk_bf16_f32 v59, v66, v67
	s_nop 1
	v_mov_b64_e32 v[60:61], v[206:207]
	v_mov_b64_e32 v[62:63], v[208:209]
	v_mul_f32_e32 v70, v73, v73
	v_mul_f32_e32 v71, v75, v75
	v_fmac_f32_e32 v70, v72, v72
	v_fmac_f32_e32 v65, v64, v64
	v_mul_f32_e32 v67, v67, v67
	v_fmac_f32_e32 v71, v74, v74
	v_add_f32_e32 v64, v70, v65
	v_fmac_f32_e32 v67, v66, v66
	v_add_f32_e32 v64, v71, v64
	v_add_f32_e32 v70, v67, v64
	v_lshlrev_b32_e32 v64, 16, v60
	v_and_b32_e32 v65, 0xffff0000, v60
	v_lshlrev_b32_e32 v60, 16, v61
	v_and_b32_e32 v61, 0xffff0000, v61
	v_lshlrev_b32_e32 v66, 16, v62
	v_and_b32_e32 v67, 0xffff0000, v62
	v_lshlrev_b32_e32 v62, 16, v63
	v_and_b32_e32 v63, 0xffff0000, v63
	v_pk_add_f32 v[54:55], v[54:55], v[60:61]
	v_pk_add_f32 v[52:53], v[52:53], v[64:65]
	v_pk_add_f32 v[60:61], v[50:51], v[62:63]
	v_pk_add_f32 v[62:63], v[48:49], v[66:67]
	v_mul_f32_e32 v48, v53, v53
	v_mul_f32_e32 v49, v55, v55
	v_mul_f32_e32 v50, v63, v63
	v_fmac_f32_e32 v48, v52, v52
	v_fmac_f32_e32 v49, v54, v54
	v_mul_f32_e32 v51, v61, v61
	v_fmac_f32_e32 v50, v62, v62
	v_add_f32_e32 v48, v48, v49
	v_add_f32_e32 v48, v50, v48
	v_fmac_f32_e32 v51, v60, v60
	v_add_f32_e32 v48, v51, v48
	v_add_f32_e32 v51, v70, v48
	ds_bpermute_b32 v66, v114, v51
	v_lshl_add_u64 v[48:49], s[44:45], 0, v[68:69]
	v_lshl_add_u64 v[64:65], v[48:49], 0, v[138:139]
	global_store_dwordx4 v[64:65], v[56:59], off
	v_cvt_pk_bf16_f32 v50, v52, v53
	s_waitcnt lgkmcnt(0)
	v_add_f32_e32 v48, v51, v66
	ds_bpermute_b32 v49, v115, v48
	v_cvt_pk_bf16_f32 v51, v54, v55
	v_cvt_pk_bf16_f32 v52, v62, v63
	v_cvt_pk_bf16_f32 v53, v60, v61
	global_store_dwordx4 v[64:65], v[50:53], off offset:256
	s_and_saveexec_b64 s[56:57], s[38:39]
	s_cbranch_execz .LBB0_1052
	s_waitcnt lgkmcnt(0)
	v_add_f32_e32 v48, v48, v49
	global_atomic_add_f32 v[112:113], v48, off offset:512
.LBB0_1052:
	s_or_b64 exec, exec, s[56:57]
	s_mov_b64 s[10:11], 0x48000
	v_lshl_add_u64 v[52:53], v[140:141], 0, s[10:11]
	s_waitcnt lgkmcnt(0)
	v_lshl_add_u64 v[48:49], s[42:43], 0, v[52:53]
	v_lshl_add_u64 v[54:55], v[48:49], 0, v[138:139]
	s_nop 1
	v_mov_b64_e32 v[48:49], v[210:211]
	v_mov_b64_e32 v[50:51], v[212:213]
	v_lshlrev_b32_e32 v56, 16, v48
	v_and_b32_e32 v57, 0xffff0000, v48
	v_lshlrev_b32_e32 v48, 16, v49
	v_and_b32_e32 v49, 0xffff0000, v49
	v_lshlrev_b32_e32 v58, 16, v50
	v_and_b32_e32 v59, 0xffff0000, v50
	v_lshlrev_b32_e32 v50, 16, v51
	v_and_b32_e32 v51, 0xffff0000, v51
	v_pk_add_f32 v[48:49], v[46:47], v[48:49]
	v_pk_add_f32 v[56:57], v[44:45], v[56:57]
	v_pk_add_f32 v[50:51], v[42:43], v[50:51]
	v_pk_add_f32 v[58:59], v[40:41], v[58:59]
	v_cvt_pk_bf16_f32 v40, v56, v57
	v_cvt_pk_bf16_f32 v41, v48, v49
	v_mul_f32_e32 v49, v49, v49
	v_cvt_pk_bf16_f32 v42, v58, v59
	v_cvt_pk_bf16_f32 v43, v50, v51
	s_nop 1
	v_mov_b64_e32 v[44:45], v[214:215]
	v_mov_b64_e32 v[46:47], v[216:217]
	v_mul_f32_e32 v54, v57, v57
	v_mul_f32_e32 v55, v59, v59
	v_fmac_f32_e32 v54, v56, v56
	v_fmac_f32_e32 v49, v48, v48
	v_mul_f32_e32 v51, v51, v51
	v_fmac_f32_e32 v55, v58, v58
	v_add_f32_e32 v48, v54, v49
	v_fmac_f32_e32 v51, v50, v50
	v_add_f32_e32 v48, v55, v48
	v_add_f32_e32 v54, v51, v48
	v_lshlrev_b32_e32 v48, 16, v44
	v_and_b32_e32 v49, 0xffff0000, v44
	v_lshlrev_b32_e32 v44, 16, v45
	v_and_b32_e32 v45, 0xffff0000, v45
	v_lshlrev_b32_e32 v50, 16, v46
	v_and_b32_e32 v51, 0xffff0000, v46
	v_lshlrev_b32_e32 v46, 16, v47
	v_and_b32_e32 v47, 0xffff0000, v47
	v_pk_add_f32 v[38:39], v[38:39], v[44:45]
	v_pk_add_f32 v[36:37], v[36:37], v[48:49]
	v_pk_add_f32 v[44:45], v[34:35], v[46:47]
	v_pk_add_f32 v[46:47], v[32:33], v[50:51]
	v_mul_f32_e32 v32, v37, v37
	v_mul_f32_e32 v33, v39, v39
	v_mul_f32_e32 v34, v47, v47
	v_fmac_f32_e32 v32, v36, v36
	v_fmac_f32_e32 v33, v38, v38
	v_mul_f32_e32 v35, v45, v45
	v_fmac_f32_e32 v34, v46, v46
	v_add_f32_e32 v32, v32, v33
	v_add_f32_e32 v32, v34, v32
	v_fmac_f32_e32 v35, v44, v44
	v_add_f32_e32 v32, v35, v32
	v_add_f32_e32 v35, v54, v32
	ds_bpermute_b32 v50, v114, v35
	v_lshl_add_u64 v[32:33], s[44:45], 0, v[52:53]
	v_lshl_add_u64 v[48:49], v[32:33], 0, v[138:139]
	global_store_dwordx4 v[48:49], v[40:43], off
	v_cvt_pk_bf16_f32 v34, v36, v37
	s_waitcnt lgkmcnt(0)
	v_add_f32_e32 v32, v35, v50
	ds_bpermute_b32 v33, v115, v32
	v_cvt_pk_bf16_f32 v35, v38, v39
	v_cvt_pk_bf16_f32 v36, v46, v47
	v_cvt_pk_bf16_f32 v37, v44, v45
	global_store_dwordx4 v[48:49], v[34:37], off offset:256
	s_and_saveexec_b64 s[56:57], s[38:39]
	s_cbranch_execz .LBB0_1054
	s_waitcnt lgkmcnt(0)
	v_add_f32_e32 v32, v32, v33
	global_atomic_add_f32 v[112:113], v32, off offset:576
.LBB0_1054:
	s_or_b64 exec, exec, s[56:57]
	s_mov_b64 s[10:11], 0x50000
	v_lshl_add_u64 v[36:37], v[140:141], 0, s[10:11]
	s_waitcnt lgkmcnt(0)
	v_lshl_add_u64 v[32:33], s[42:43], 0, v[36:37]
	v_lshl_add_u64 v[38:39], v[32:33], 0, v[138:139]
	s_nop 1
	v_mov_b64_e32 v[32:33], v[218:219]
	v_mov_b64_e32 v[34:35], v[220:221]
	v_lshlrev_b32_e32 v40, 16, v32
	v_and_b32_e32 v41, 0xffff0000, v32
	v_lshlrev_b32_e32 v32, 16, v33
	v_and_b32_e32 v33, 0xffff0000, v33
	v_lshlrev_b32_e32 v42, 16, v34
	v_and_b32_e32 v43, 0xffff0000, v34
	v_lshlrev_b32_e32 v34, 16, v35
	v_and_b32_e32 v35, 0xffff0000, v35
	v_pk_add_f32 v[32:33], v[30:31], v[32:33]
	v_pk_add_f32 v[40:41], v[28:29], v[40:41]
	v_pk_add_f32 v[34:35], v[26:27], v[34:35]
	v_pk_add_f32 v[42:43], v[24:25], v[42:43]
	v_cvt_pk_bf16_f32 v24, v40, v41
	v_cvt_pk_bf16_f32 v25, v32, v33
	v_mul_f32_e32 v33, v33, v33
	v_cvt_pk_bf16_f32 v26, v42, v43
	v_cvt_pk_bf16_f32 v27, v34, v35
	s_nop 1
	v_mov_b64_e32 v[28:29], v[222:223]
	v_mov_b64_e32 v[30:31], v[224:225]
	v_mul_f32_e32 v38, v41, v41
	v_mul_f32_e32 v39, v43, v43
	v_fmac_f32_e32 v38, v40, v40
	v_fmac_f32_e32 v33, v32, v32
	v_mul_f32_e32 v35, v35, v35
	v_fmac_f32_e32 v39, v42, v42
	v_add_f32_e32 v32, v38, v33
	v_fmac_f32_e32 v35, v34, v34
	v_add_f32_e32 v32, v39, v32
	v_add_f32_e32 v38, v35, v32
	v_lshlrev_b32_e32 v32, 16, v28
	v_and_b32_e32 v33, 0xffff0000, v28
	v_lshlrev_b32_e32 v28, 16, v29
	v_and_b32_e32 v29, 0xffff0000, v29
	v_lshlrev_b32_e32 v34, 16, v30
	v_and_b32_e32 v35, 0xffff0000, v30
	v_lshlrev_b32_e32 v30, 16, v31
	v_and_b32_e32 v31, 0xffff0000, v31
	v_pk_add_f32 v[22:23], v[22:23], v[28:29]
	v_pk_add_f32 v[20:21], v[20:21], v[32:33]
	v_pk_add_f32 v[28:29], v[18:19], v[30:31]
	v_pk_add_f32 v[30:31], v[16:17], v[34:35]
	v_mul_f32_e32 v16, v21, v21
	v_mul_f32_e32 v17, v23, v23
	v_mul_f32_e32 v18, v31, v31
	v_fmac_f32_e32 v16, v20, v20
	v_fmac_f32_e32 v17, v22, v22
	v_mul_f32_e32 v19, v29, v29
	v_fmac_f32_e32 v18, v30, v30
	v_add_f32_e32 v16, v16, v17
	v_add_f32_e32 v16, v18, v16
	v_fmac_f32_e32 v19, v28, v28
	v_add_f32_e32 v16, v19, v16
	v_add_f32_e32 v19, v38, v16
	ds_bpermute_b32 v34, v114, v19
	v_lshl_add_u64 v[16:17], s[44:45], 0, v[36:37]
	v_lshl_add_u64 v[32:33], v[16:17], 0, v[138:139]
	global_store_dwordx4 v[32:33], v[24:27], off
	v_cvt_pk_bf16_f32 v18, v20, v21
	s_waitcnt lgkmcnt(0)
	v_add_f32_e32 v16, v19, v34
	ds_bpermute_b32 v17, v115, v16
	v_cvt_pk_bf16_f32 v19, v22, v23
	v_cvt_pk_bf16_f32 v20, v30, v31
	v_cvt_pk_bf16_f32 v21, v28, v29
	global_store_dwordx4 v[32:33], v[18:21], off offset:256
	s_and_saveexec_b64 s[56:57], s[38:39]
	s_cbranch_execz .LBB0_1056
	s_waitcnt lgkmcnt(0)
	v_add_f32_e32 v16, v16, v17
	global_atomic_add_f32 v[112:113], v16, off offset:640
.LBB0_1056:
	s_or_b64 exec, exec, s[56:57]
	s_mov_b64 s[10:11], 0x58000
	v_lshl_add_u64 v[20:21], v[140:141], 0, s[10:11]
	s_waitcnt lgkmcnt(0)
	v_lshl_add_u64 v[16:17], s[42:43], 0, v[20:21]
	v_lshl_add_u64 v[22:23], v[16:17], 0, v[138:139]
	s_nop 1
	v_mov_b64_e32 v[16:17], v[226:227]
	v_mov_b64_e32 v[18:19], v[228:229]
	v_lshlrev_b32_e32 v24, 16, v16
	v_and_b32_e32 v25, 0xffff0000, v16
	v_lshlrev_b32_e32 v16, 16, v17
	v_and_b32_e32 v17, 0xffff0000, v17
	v_lshlrev_b32_e32 v26, 16, v18
	v_and_b32_e32 v27, 0xffff0000, v18
	v_lshlrev_b32_e32 v18, 16, v19
	v_and_b32_e32 v19, 0xffff0000, v19
	v_pk_add_f32 v[16:17], v[14:15], v[16:17]
	v_pk_add_f32 v[24:25], v[12:13], v[24:25]
	v_pk_add_f32 v[18:19], v[10:11], v[18:19]
	v_pk_add_f32 v[26:27], v[8:9], v[26:27]
	v_cvt_pk_bf16_f32 v8, v24, v25
	v_cvt_pk_bf16_f32 v9, v16, v17
	v_mul_f32_e32 v17, v17, v17
	v_cvt_pk_bf16_f32 v10, v26, v27
	v_cvt_pk_bf16_f32 v11, v18, v19
	s_nop 1
	v_mov_b64_e32 v[12:13], v[230:231]
	v_mov_b64_e32 v[14:15], v[232:233]
	v_mul_f32_e32 v22, v25, v25
	v_mul_f32_e32 v23, v27, v27
	v_fmac_f32_e32 v22, v24, v24
	v_fmac_f32_e32 v17, v16, v16
	v_mul_f32_e32 v19, v19, v19
	v_fmac_f32_e32 v23, v26, v26
	v_add_f32_e32 v16, v22, v17
	v_fmac_f32_e32 v19, v18, v18
	v_add_f32_e32 v16, v23, v16
	v_add_f32_e32 v22, v19, v16
	v_lshlrev_b32_e32 v16, 16, v12
	v_and_b32_e32 v17, 0xffff0000, v12
	v_lshlrev_b32_e32 v12, 16, v13
	v_and_b32_e32 v13, 0xffff0000, v13
	v_lshlrev_b32_e32 v18, 16, v14
	v_and_b32_e32 v19, 0xffff0000, v14
	v_lshlrev_b32_e32 v14, 16, v15
	v_and_b32_e32 v15, 0xffff0000, v15
	v_pk_add_f32 v[6:7], v[6:7], v[12:13]
	v_pk_add_f32 v[4:5], v[4:5], v[16:17]
	v_pk_add_f32 v[12:13], v[2:3], v[14:15]
	v_pk_add_f32 v[14:15], v[0:1], v[18:19]
	v_mul_f32_e32 v0, v5, v5
	v_mul_f32_e32 v1, v7, v7
	v_mul_f32_e32 v2, v15, v15
	v_fmac_f32_e32 v0, v4, v4
	v_fmac_f32_e32 v1, v6, v6
	v_mul_f32_e32 v3, v13, v13
	v_fmac_f32_e32 v2, v14, v14
	v_add_f32_e32 v0, v0, v1
	v_add_f32_e32 v0, v2, v0
	v_fmac_f32_e32 v3, v12, v12
	v_add_f32_e32 v0, v3, v0
	v_add_f32_e32 v3, v22, v0
	ds_bpermute_b32 v18, v114, v3
	v_lshl_add_u64 v[0:1], s[44:45], 0, v[20:21]
	v_lshl_add_u64 v[16:17], v[0:1], 0, v[138:139]
	global_store_dwordx4 v[16:17], v[8:11], off
	v_cvt_pk_bf16_f32 v2, v4, v5
	s_waitcnt lgkmcnt(0)
	v_add_f32_e32 v0, v3, v18
	ds_bpermute_b32 v1, v115, v0
	v_cvt_pk_bf16_f32 v3, v6, v7
	v_cvt_pk_bf16_f32 v4, v14, v15
	v_cvt_pk_bf16_f32 v5, v12, v13
	global_store_dwordx4 v[16:17], v[2:5], off offset:256
	s_and_saveexec_b64 s[56:57], s[38:39]
	s_cbranch_execz .LBB0_1058
	s_waitcnt lgkmcnt(0)
	v_add_f32_e32 v0, v0, v1
	global_atomic_add_f32 v[112:113], v0, off offset:704

.LBB0_1232:
	v_lshl_add_u32 v140, s52, 8, v144
	v_lshl_or_b32 v138, s54, 8, v146
	v_ashrrev_i32_e32 v141, 31, v140
	v_ashrrev_i32_e32 v139, 31, v138
	v_lshlrev_b64 v[152:153], 11, v[140:141]
	v_lshl_add_u64 v[148:149], s[22:23], 0, v[152:153]
	v_lshlrev_b64 v[138:139], 1, v[138:139]
	v_lshl_add_u64 v[154:155], v[148:149], 0, v[138:139]
	global_load_dwordx4 v[148:151], v[154:155], off
	global_load_dwordx4 v[160:163], v[154:155], off offset:256
	v_add_co_u32_e32 v230, vcc, 0x8000, v154
	s_nop 1
	v_addc_co_u32_e32 v231, vcc, 0, v155, vcc
	global_load_dwordx4 v[164:167], v[230:231], off
	global_load_dwordx4 v[168:171], v[230:231], off offset:256
	v_add_co_u32_e32 v230, vcc, 0x10000, v154
	s_nop 1
	v_addc_co_u32_e32 v231, vcc, 0, v155, vcc
	global_load_dwordx4 v[172:175], v[230:231], off
	global_load_dwordx4 v[176:179], v[230:231], off offset:256
	v_add_co_u32_e32 v230, vcc, 0x18000, v154
	s_nop 1
	v_addc_co_u32_e32 v231, vcc, 0, v155, vcc
	global_load_dwordx4 v[180:183], v[230:231], off
	global_load_dwordx4 v[184:187], v[230:231], off offset:256
	v_add_co_u32_e32 v230, vcc, 0x40000, v154
	s_nop 1
	v_addc_co_u32_e32 v231, vcc, 0, v155, vcc
	global_load_dwordx4 v[188:191], v[230:231], off
	global_load_dwordx4 v[206:209], v[230:231], off offset:256
	v_add_co_u32_e32 v230, vcc, 0x48000, v154
	s_nop 1
	v_addc_co_u32_e32 v231, vcc, 0, v155, vcc
	global_load_dwordx4 v[210:213], v[230:231], off
	global_load_dwordx4 v[214:217], v[230:231], off offset:256
	v_add_co_u32_e32 v230, vcc, 0x50000, v154
	s_nop 1
	v_addc_co_u32_e32 v231, vcc, 0, v155, vcc
	global_load_dwordx4 v[218:221], v[230:231], off
	global_load_dwordx4 v[222:225], v[230:231], off offset:256
	v_add_co_u32_e32 v230, vcc, 0x58000, v154
	s_nop 1
	v_addc_co_u32_e32 v231, vcc, 0, v155, vcc
	global_load_dwordx4 v[226:229], v[230:231], off
	global_load_dwordx4 v[230:233], v[230:231], off offset:256
	s_waitcnt vmcnt(0)
	v_lshlrev_b32_e32 v156, 16, v148
	v_and_b32_e32 v157, 0xffff0000, v148
	v_lshlrev_b32_e32 v148, 16, v149
	v_and_b32_e32 v149, 0xffff0000, v149
	v_lshlrev_b32_e32 v158, 16, v150
	v_and_b32_e32 v159, 0xffff0000, v150
	v_lshlrev_b32_e32 v150, 16, v151
	v_and_b32_e32 v151, 0xffff0000, v151
	v_pk_add_f32 v[126:127], v[126:127], v[148:149]
	v_pk_add_f32 v[124:125], v[124:125], v[156:157]
	v_pk_add_f32 v[148:149], v[122:123], v[150:151]
	v_pk_add_f32 v[122:123], v[120:121], v[158:159]
	v_mul_f32_e32 v120, v125, v125
	v_mul_f32_e32 v121, v127, v127
	v_fmac_f32_e32 v120, v124, v124
	v_fmac_f32_e32 v121, v126, v126
	v_add_f32_e32 v120, v120, v121
	v_mul_f32_e32 v121, v123, v123
	v_fmac_f32_e32 v121, v122, v122
	v_add_f32_e32 v120, v121, v120
	v_mul_f32_e32 v121, v149, v149
	v_fmac_f32_e32 v121, v148, v148
	v_add_f32_e32 v150, v121, v120
	v_cvt_pk_bf16_f32 v120, v124, v125
	v_lshl_add_u64 v[124:125], s[30:31], 0, v[152:153]
	v_cvt_pk_bf16_f32 v121, v126, v127
	v_cvt_pk_bf16_f32 v122, v122, v123
	v_cvt_pk_bf16_f32 v123, v148, v149
	v_lshl_add_u64 v[124:125], v[124:125], 0, v[138:139]
	global_store_dwordx4 v[124:125], v[120:123], off
	s_nop 1
	v_mov_b64_e32 v[120:121], v[160:161]
	v_mov_b64_e32 v[122:123], v[162:163]
	v_lshlrev_b32_e32 v126, 16, v120
	v_and_b32_e32 v127, 0xffff0000, v120
	v_lshlrev_b32_e32 v120, 16, v121
	v_and_b32_e32 v121, 0xffff0000, v121
	v_lshlrev_b32_e32 v148, 16, v122
	v_and_b32_e32 v149, 0xffff0000, v122
	v_lshlrev_b32_e32 v122, 16, v123
	v_and_b32_e32 v123, 0xffff0000, v123
	v_pk_add_f32 v[118:119], v[118:119], v[120:121]
	v_pk_add_f32 v[116:117], v[116:117], v[126:127]
	v_pk_add_f32 v[120:121], v[114:115], v[122:123]
	v_pk_add_f32 v[114:115], v[112:113], v[148:149]
	v_mul_f32_e32 v112, v117, v117
	v_mul_f32_e32 v113, v119, v119
	v_fmac_f32_e32 v112, v116, v116
	v_fmac_f32_e32 v113, v118, v118
	v_add_f32_e32 v112, v112, v113
	v_mul_f32_e32 v113, v115, v115
	v_fmac_f32_e32 v113, v114, v114
	v_add_f32_e32 v112, v113, v112
	v_mul_f32_e32 v113, v121, v121
	v_fmac_f32_e32 v113, v120, v120
	v_add_f32_e32 v112, v113, v112
	v_add_f32_e32 v122, v150, v112
	v_cvt_pk_bf16_f32 v112, v116, v117
	v_cvt_pk_bf16_f32 v113, v118, v119
	v_cvt_pk_bf16_f32 v114, v114, v115
	v_cvt_pk_bf16_f32 v115, v120, v121
	global_store_dwordx4 v[124:125], v[112:115], off offset:256
	s_nop 1
	v_mbcnt_hi_u32_b32 v113, -1, v234
	v_and_b32_e32 v114, 64, v113
	v_xor_b32_e32 v112, 16, v113
	v_add_u32_e32 v115, 64, v114
	v_cmp_lt_i32_e32 vcc, v112, v115
	v_xor_b32_e32 v116, 32, v113
	s_nop 0
	v_cndmask_b32_e32 v112, v113, v112, vcc
	v_lshlrev_b32_e32 v114, 2, v112
	ds_bpermute_b32 v112, v114, v122
	v_cmp_lt_i32_e32 vcc, v116, v115
	s_waitcnt lgkmcnt(0)
	v_add_f32_e32 v112, v122, v112
	v_cndmask_b32_e32 v113, v113, v116, vcc
	v_lshlrev_b32_e32 v115, 2, v113
	ds_bpermute_b32 v113, v115, v112
	s_and_saveexec_b64 s[52:53], s[38:39]
	s_cbranch_execz .LBB0_1234
	v_lshl_add_u64 v[116:117], v[140:141], 2, s[36:37]
	s_waitcnt lgkmcnt(0)
	v_add_f32_e32 v112, v112, v113
	global_atomic_add_f32 v[116:117], v112, off
.LBB0_1234:
	s_or_b64 exec, exec, s[52:53]
	v_or_b32_e32 v112, 16, v140
	s_waitcnt lgkmcnt(0)
	v_ashrrev_i32_e32 v113, 31, v112
	v_lshlrev_b64 v[120:121], 11, v[112:113]
	v_lshl_add_u64 v[116:117], s[22:23], 0, v[120:121]
	v_lshl_add_u64 v[122:123], v[116:117], 0, v[138:139]
	s_nop 1
	v_mov_b64_e32 v[116:117], v[164:165]
	v_mov_b64_e32 v[118:119], v[166:167]
	v_lshlrev_b32_e32 v124, 16, v116
	v_and_b32_e32 v125, 0xffff0000, v116
	v_lshlrev_b32_e32 v116, 16, v117
	v_and_b32_e32 v117, 0xffff0000, v117
	v_lshlrev_b32_e32 v126, 16, v118
	v_and_b32_e32 v127, 0xffff0000, v118
	v_lshlrev_b32_e32 v118, 16, v119
	v_and_b32_e32 v119, 0xffff0000, v119
	v_pk_add_f32 v[116:117], v[110:111], v[116:117]
	v_pk_add_f32 v[124:125], v[108:109], v[124:125]
	v_pk_add_f32 v[118:119], v[106:107], v[118:119]
	v_pk_add_f32 v[126:127], v[104:105], v[126:127]
	v_cvt_pk_bf16_f32 v104, v124, v125
	v_cvt_pk_bf16_f32 v105, v116, v117
	v_mul_f32_e32 v117, v117, v117
	v_cvt_pk_bf16_f32 v106, v126, v127
	v_cvt_pk_bf16_f32 v107, v118, v119
	s_nop 1
	v_mov_b64_e32 v[108:109], v[168:169]
	v_mov_b64_e32 v[110:111], v[170:171]
	v_mul_f32_e32 v122, v125, v125
	v_mul_f32_e32 v123, v127, v127
	v_fmac_f32_e32 v122, v124, v124
	v_fmac_f32_e32 v117, v116, v116
	v_mul_f32_e32 v119, v119, v119
	v_fmac_f32_e32 v123, v126, v126
	v_add_f32_e32 v116, v122, v117
	v_fmac_f32_e32 v119, v118, v118
	v_add_f32_e32 v116, v123, v116
	v_add_f32_e32 v122, v119, v116
	v_lshlrev_b32_e32 v116, 16, v108
	v_and_b32_e32 v117, 0xffff0000, v108
	v_lshlrev_b32_e32 v108, 16, v109
	v_and_b32_e32 v109, 0xffff0000, v109
	v_lshlrev_b32_e32 v118, 16, v110
	v_and_b32_e32 v119, 0xffff0000, v110
	v_lshlrev_b32_e32 v110, 16, v111
	v_and_b32_e32 v111, 0xffff0000, v111
	v_pk_add_f32 v[102:103], v[102:103], v[108:109]
	v_pk_add_f32 v[100:101], v[100:101], v[116:117]
	v_pk_add_f32 v[108:109], v[98:99], v[110:111]
	v_pk_add_f32 v[110:111], v[96:97], v[118:119]
	v_mul_f32_e32 v96, v101, v101
	v_mul_f32_e32 v97, v103, v103
	v_mul_f32_e32 v98, v111, v111
	v_fmac_f32_e32 v96, v100, v100
	v_fmac_f32_e32 v97, v102, v102
	v_mul_f32_e32 v99, v109, v109
	v_fmac_f32_e32 v98, v110, v110
	v_add_f32_e32 v96, v96, v97
	v_add_f32_e32 v96, v98, v96
	v_fmac_f32_e32 v99, v108, v108
	v_add_f32_e32 v96, v99, v96
	v_add_f32_e32 v99, v122, v96
	ds_bpermute_b32 v118, v114, v99
	v_lshl_add_u64 v[96:97], s[30:31], 0, v[120:121]
	v_lshl_add_u64 v[116:117], v[96:97], 0, v[138:139]
	global_store_dwordx4 v[116:117], v[104:107], off
	v_cvt_pk_bf16_f32 v98, v100, v101
	s_waitcnt lgkmcnt(0)
	v_add_f32_e32 v96, v99, v118
	ds_bpermute_b32 v97, v115, v96
	v_cvt_pk_bf16_f32 v99, v102, v103
	v_cvt_pk_bf16_f32 v100, v110, v111
	v_cvt_pk_bf16_f32 v101, v108, v109
	global_store_dwordx4 v[116:117], v[98:101], off offset:256
	s_and_saveexec_b64 s[52:53], s[38:39]
	s_cbranch_execz .LBB0_1236
	v_lshl_add_u64 v[98:99], v[112:113], 2, s[36:37]
	s_waitcnt lgkmcnt(0)
	v_add_f32_e32 v96, v96, v97
	global_atomic_add_f32 v[98:99], v96, off
.LBB0_1236:
	s_or_b64 exec, exec, s[52:53]
	v_or_b32_e32 v96, 32, v140
	s_waitcnt lgkmcnt(0)
	v_ashrrev_i32_e32 v97, 31, v96
	v_lshlrev_b64 v[102:103], 11, v[96:97]
	v_lshl_add_u64 v[98:99], s[22:23], 0, v[102:103]
	v_lshl_add_u64 v[104:105], v[98:99], 0, v[138:139]
	s_nop 1
	v_mov_b64_e32 v[98:99], v[172:173]
	v_mov_b64_e32 v[100:101], v[174:175]
	v_lshlrev_b32_e32 v106, 16, v98
	v_and_b32_e32 v107, 0xffff0000, v98
	v_lshlrev_b32_e32 v98, 16, v99
	v_and_b32_e32 v99, 0xffff0000, v99
	v_lshlrev_b32_e32 v108, 16, v100
	v_and_b32_e32 v109, 0xffff0000, v100
	v_lshlrev_b32_e32 v100, 16, v101
	v_and_b32_e32 v101, 0xffff0000, v101
	v_pk_add_f32 v[98:99], v[94:95], v[98:99]
	v_pk_add_f32 v[106:107], v[92:93], v[106:107]
	v_pk_add_f32 v[100:101], v[90:91], v[100:101]
	v_pk_add_f32 v[108:109], v[88:89], v[108:109]
	v_cvt_pk_bf16_f32 v88, v106, v107
	v_cvt_pk_bf16_f32 v89, v98, v99
	v_mul_f32_e32 v99, v99, v99
	v_cvt_pk_bf16_f32 v90, v108, v109
	v_cvt_pk_bf16_f32 v91, v100, v101
	s_nop 1
	v_mov_b64_e32 v[92:93], v[176:177]
	v_mov_b64_e32 v[94:95], v[178:179]
	v_mul_f32_e32 v104, v107, v107
	v_mul_f32_e32 v105, v109, v109
	v_fmac_f32_e32 v104, v106, v106
	v_fmac_f32_e32 v99, v98, v98
	v_mul_f32_e32 v101, v101, v101
	v_fmac_f32_e32 v105, v108, v108
	v_add_f32_e32 v98, v104, v99
	v_fmac_f32_e32 v101, v100, v100
	v_add_f32_e32 v98, v105, v98
	v_add_f32_e32 v104, v101, v98
	v_lshlrev_b32_e32 v98, 16, v92
	v_and_b32_e32 v99, 0xffff0000, v92
	v_lshlrev_b32_e32 v92, 16, v93
	v_and_b32_e32 v93, 0xffff0000, v93
	v_lshlrev_b32_e32 v100, 16, v94
	v_and_b32_e32 v101, 0xffff0000, v94
	v_lshlrev_b32_e32 v94, 16, v95
	v_and_b32_e32 v95, 0xffff0000, v95
	v_pk_add_f32 v[86:87], v[86:87], v[92:93]
	v_pk_add_f32 v[84:85], v[84:85], v[98:99]
	v_pk_add_f32 v[92:93], v[82:83], v[94:95]
	v_pk_add_f32 v[94:95], v[80:81], v[100:101]
	v_mul_f32_e32 v80, v85, v85
	v_mul_f32_e32 v81, v87, v87
	v_mul_f32_e32 v82, v95, v95
	v_fmac_f32_e32 v80, v84, v84
	v_fmac_f32_e32 v81, v86, v86
	v_mul_f32_e32 v83, v93, v93
	v_fmac_f32_e32 v82, v94, v94
	v_add_f32_e32 v80, v80, v81
	v_add_f32_e32 v80, v82, v80
	v_fmac_f32_e32 v83, v92, v92
	v_add_f32_e32 v80, v83, v80
	v_add_f32_e32 v83, v104, v80
	ds_bpermute_b32 v100, v114, v83
	v_lshl_add_u64 v[80:81], s[30:31], 0, v[102:103]
	v_lshl_add_u64 v[98:99], v[80:81], 0, v[138:139]
	global_store_dwordx4 v[98:99], v[88:91], off
	v_cvt_pk_bf16_f32 v82, v84, v85
	s_waitcnt lgkmcnt(0)
	v_add_f32_e32 v80, v83, v100
	ds_bpermute_b32 v81, v115, v80
	v_cvt_pk_bf16_f32 v83, v86, v87
	v_cvt_pk_bf16_f32 v84, v94, v95
	v_cvt_pk_bf16_f32 v85, v92, v93
	global_store_dwordx4 v[98:99], v[82:85], off offset:256
	s_and_saveexec_b64 s[52:53], s[38:39]
	s_cbranch_execz .LBB0_1238
	v_lshl_add_u64 v[82:83], v[96:97], 2, s[36:37]
	s_waitcnt lgkmcnt(0)
	v_add_f32_e32 v80, v80, v81
	global_atomic_add_f32 v[82:83], v80, off
.LBB0_1238:
	s_or_b64 exec, exec, s[52:53]
	v_or_b32_e32 v80, 48, v140
	s_waitcnt lgkmcnt(0)
	v_ashrrev_i32_e32 v81, 31, v80
	v_lshlrev_b64 v[86:87], 11, v[80:81]
	v_lshl_add_u64 v[82:83], s[22:23], 0, v[86:87]
	v_lshl_add_u64 v[88:89], v[82:83], 0, v[138:139]
	s_nop 1
	v_mov_b64_e32 v[82:83], v[180:181]
	v_mov_b64_e32 v[84:85], v[182:183]
	v_lshlrev_b32_e32 v90, 16, v82
	v_and_b32_e32 v91, 0xffff0000, v82
	v_lshlrev_b32_e32 v82, 16, v83
	v_and_b32_e32 v83, 0xffff0000, v83
	v_lshlrev_b32_e32 v92, 16, v84
	v_and_b32_e32 v93, 0xffff0000, v84
	v_lshlrev_b32_e32 v84, 16, v85
	v_and_b32_e32 v85, 0xffff0000, v85
	v_pk_add_f32 v[82:83], v[78:79], v[82:83]
	v_pk_add_f32 v[90:91], v[76:77], v[90:91]
	v_pk_add_f32 v[84:85], v[74:75], v[84:85]
	v_pk_add_f32 v[92:93], v[72:73], v[92:93]
	v_cvt_pk_bf16_f32 v72, v90, v91
	v_cvt_pk_bf16_f32 v73, v82, v83
	v_mul_f32_e32 v83, v83, v83
	v_cvt_pk_bf16_f32 v74, v92, v93
	v_cvt_pk_bf16_f32 v75, v84, v85
	s_nop 1
	v_mov_b64_e32 v[76:77], v[184:185]
	v_mov_b64_e32 v[78:79], v[186:187]
	v_mul_f32_e32 v88, v91, v91
	v_mul_f32_e32 v89, v93, v93
	v_fmac_f32_e32 v88, v90, v90
	v_fmac_f32_e32 v83, v82, v82
	v_mul_f32_e32 v85, v85, v85
	v_fmac_f32_e32 v89, v92, v92
	v_add_f32_e32 v82, v88, v83
	v_fmac_f32_e32 v85, v84, v84
	v_add_f32_e32 v82, v89, v82
	v_add_f32_e32 v88, v85, v82
	v_lshlrev_b32_e32 v82, 16, v76
	v_and_b32_e32 v83, 0xffff0000, v76
	v_lshlrev_b32_e32 v76, 16, v77
	v_and_b32_e32 v77, 0xffff0000, v77
	v_lshlrev_b32_e32 v84, 16, v78
	v_and_b32_e32 v85, 0xffff0000, v78
	v_lshlrev_b32_e32 v78, 16, v79
	v_and_b32_e32 v79, 0xffff0000, v79
	v_pk_add_f32 v[70:71], v[70:71], v[76:77]
	v_pk_add_f32 v[68:69], v[68:69], v[82:83]
	v_pk_add_f32 v[76:77], v[66:67], v[78:79]
	v_pk_add_f32 v[78:79], v[64:65], v[84:85]
	v_mul_f32_e32 v64, v69, v69
	v_mul_f32_e32 v65, v71, v71
	v_mul_f32_e32 v66, v79, v79
	v_fmac_f32_e32 v64, v68, v68
	v_fmac_f32_e32 v65, v70, v70
	v_mul_f32_e32 v67, v77, v77
	v_fmac_f32_e32 v66, v78, v78
	v_add_f32_e32 v64, v64, v65
	v_add_f32_e32 v64, v66, v64
	v_fmac_f32_e32 v67, v76, v76
	v_add_f32_e32 v64, v67, v64
	v_add_f32_e32 v67, v88, v64
	ds_bpermute_b32 v84, v114, v67
	v_lshl_add_u64 v[64:65], s[30:31], 0, v[86:87]
	v_lshl_add_u64 v[82:83], v[64:65], 0, v[138:139]
	global_store_dwordx4 v[82:83], v[72:75], off
	v_cvt_pk_bf16_f32 v66, v68, v69
	s_waitcnt lgkmcnt(0)
	v_add_f32_e32 v64, v67, v84
	ds_bpermute_b32 v65, v115, v64
	v_cvt_pk_bf16_f32 v67, v70, v71
	v_cvt_pk_bf16_f32 v68, v78, v79
	v_cvt_pk_bf16_f32 v69, v76, v77
	global_store_dwordx4 v[82:83], v[66:69], off offset:256
	s_and_saveexec_b64 s[52:53], s[38:39]
	s_cbranch_execz .LBB0_1240
	v_lshl_add_u64 v[66:67], v[80:81], 2, s[36:37]
	s_waitcnt lgkmcnt(0)
	v_add_f32_e32 v64, v64, v65
	global_atomic_add_f32 v[66:67], v64, off
.LBB0_1240:
	s_or_b64 exec, exec, s[52:53]
	v_add_u32_e32 v64, 0x80, v140
	s_waitcnt lgkmcnt(0)
	v_ashrrev_i32_e32 v65, 31, v64
	v_lshlrev_b64 v[70:71], 11, v[64:65]
	v_lshl_add_u64 v[66:67], s[22:23], 0, v[70:71]
	v_lshl_add_u64 v[72:73], v[66:67], 0, v[138:139]
	s_nop 1
	v_mov_b64_e32 v[66:67], v[188:189]
	v_mov_b64_e32 v[68:69], v[190:191]
	v_lshlrev_b32_e32 v74, 16, v66
	v_and_b32_e32 v75, 0xffff0000, v66
	v_lshlrev_b32_e32 v66, 16, v67
	v_and_b32_e32 v67, 0xffff0000, v67
	v_lshlrev_b32_e32 v76, 16, v68
	v_and_b32_e32 v77, 0xffff0000, v68
	v_lshlrev_b32_e32 v68, 16, v69
	v_and_b32_e32 v69, 0xffff0000, v69
	v_pk_add_f32 v[66:67], v[62:63], v[66:67]
	v_pk_add_f32 v[74:75], v[60:61], v[74:75]
	v_pk_add_f32 v[68:69], v[58:59], v[68:69]
	v_pk_add_f32 v[76:77], v[56:57], v[76:77]
	v_cvt_pk_bf16_f32 v56, v74, v75
	v_cvt_pk_bf16_f32 v57, v66, v67
	v_mul_f32_e32 v67, v67, v67
	v_cvt_pk_bf16_f32 v58, v76, v77
	v_cvt_pk_bf16_f32 v59, v68, v69
	s_nop 1
	v_mov_b64_e32 v[60:61], v[206:207]
	v_mov_b64_e32 v[62:63], v[208:209]
	v_mul_f32_e32 v72, v75, v75
	v_mul_f32_e32 v73, v77, v77
	v_fmac_f32_e32 v72, v74, v74
	v_fmac_f32_e32 v67, v66, v66
	v_mul_f32_e32 v69, v69, v69
	v_fmac_f32_e32 v73, v76, v76
	v_add_f32_e32 v66, v72, v67
	v_fmac_f32_e32 v69, v68, v68
	v_add_f32_e32 v66, v73, v66
	v_add_f32_e32 v72, v69, v66
	v_lshlrev_b32_e32 v66, 16, v60
	v_and_b32_e32 v67, 0xffff0000, v60
	v_lshlrev_b32_e32 v60, 16, v61
	v_and_b32_e32 v61, 0xffff0000, v61
	v_lshlrev_b32_e32 v68, 16, v62
	v_and_b32_e32 v69, 0xffff0000, v62
	v_lshlrev_b32_e32 v62, 16, v63
	v_and_b32_e32 v63, 0xffff0000, v63
	v_pk_add_f32 v[54:55], v[54:55], v[60:61]
	v_pk_add_f32 v[52:53], v[52:53], v[66:67]
	v_pk_add_f32 v[60:61], v[50:51], v[62:63]
	v_pk_add_f32 v[62:63], v[48:49], v[68:69]
	v_mul_f32_e32 v48, v53, v53
	v_mul_f32_e32 v49, v55, v55
	v_mul_f32_e32 v50, v63, v63
	v_fmac_f32_e32 v48, v52, v52
	v_fmac_f32_e32 v49, v54, v54
	v_mul_f32_e32 v51, v61, v61
	v_fmac_f32_e32 v50, v62, v62
	v_add_f32_e32 v48, v48, v49
	v_add_f32_e32 v48, v50, v48
	v_fmac_f32_e32 v51, v60, v60
	v_add_f32_e32 v48, v51, v48
	v_add_f32_e32 v51, v72, v48
	ds_bpermute_b32 v68, v114, v51
	v_lshl_add_u64 v[48:49], s[30:31], 0, v[70:71]
	v_lshl_add_u64 v[66:67], v[48:49], 0, v[138:139]
	global_store_dwordx4 v[66:67], v[56:59], off
	v_cvt_pk_bf16_f32 v50, v52, v53
	s_waitcnt lgkmcnt(0)
	v_add_f32_e32 v48, v51, v68
	ds_bpermute_b32 v49, v115, v48
	v_cvt_pk_bf16_f32 v51, v54, v55
	v_cvt_pk_bf16_f32 v52, v62, v63
	v_cvt_pk_bf16_f32 v53, v60, v61
	global_store_dwordx4 v[66:67], v[50:53], off offset:256
	s_and_saveexec_b64 s[52:53], s[38:39]
	s_cbranch_execz .LBB0_1242
	v_lshl_add_u64 v[50:51], v[64:65], 2, s[36:37]
	s_waitcnt lgkmcnt(0)
	v_add_f32_e32 v48, v48, v49
	global_atomic_add_f32 v[50:51], v48, off
.LBB0_1242:
	s_or_b64 exec, exec, s[52:53]
	v_add_u32_e32 v48, 0x90, v140
	s_waitcnt lgkmcnt(0)
	v_ashrrev_i32_e32 v49, 31, v48
	v_lshlrev_b64 v[54:55], 11, v[48:49]
	v_lshl_add_u64 v[50:51], s[22:23], 0, v[54:55]
	v_lshl_add_u64 v[56:57], v[50:51], 0, v[138:139]
	s_nop 1
	v_mov_b64_e32 v[50:51], v[210:211]
	v_mov_b64_e32 v[52:53], v[212:213]
	v_lshlrev_b32_e32 v58, 16, v50
	v_and_b32_e32 v59, 0xffff0000, v50
	v_lshlrev_b32_e32 v50, 16, v51
	v_and_b32_e32 v51, 0xffff0000, v51
	v_lshlrev_b32_e32 v60, 16, v52
	v_and_b32_e32 v61, 0xffff0000, v52
	v_lshlrev_b32_e32 v52, 16, v53
	v_and_b32_e32 v53, 0xffff0000, v53
	v_pk_add_f32 v[50:51], v[46:47], v[50:51]
	v_pk_add_f32 v[58:59], v[44:45], v[58:59]
	v_pk_add_f32 v[52:53], v[42:43], v[52:53]
	v_pk_add_f32 v[60:61], v[40:41], v[60:61]
	v_cvt_pk_bf16_f32 v40, v58, v59
	v_cvt_pk_bf16_f32 v41, v50, v51
	v_mul_f32_e32 v51, v51, v51
	v_cvt_pk_bf16_f32 v42, v60, v61
	v_cvt_pk_bf16_f32 v43, v52, v53
	s_nop 1
	v_mov_b64_e32 v[44:45], v[214:215]
	v_mov_b64_e32 v[46:47], v[216:217]
	v_mul_f32_e32 v56, v59, v59
	v_mul_f32_e32 v57, v61, v61
	v_fmac_f32_e32 v56, v58, v58
	v_fmac_f32_e32 v51, v50, v50
	v_mul_f32_e32 v53, v53, v53
	v_fmac_f32_e32 v57, v60, v60
	v_add_f32_e32 v50, v56, v51
	v_fmac_f32_e32 v53, v52, v52
	v_add_f32_e32 v50, v57, v50
	v_add_f32_e32 v56, v53, v50
	v_lshlrev_b32_e32 v50, 16, v44
	v_and_b32_e32 v51, 0xffff0000, v44
	v_lshlrev_b32_e32 v44, 16, v45
	v_and_b32_e32 v45, 0xffff0000, v45
	v_lshlrev_b32_e32 v52, 16, v46
	v_and_b32_e32 v53, 0xffff0000, v46
	v_lshlrev_b32_e32 v46, 16, v47
	v_and_b32_e32 v47, 0xffff0000, v47
	v_pk_add_f32 v[38:39], v[38:39], v[44:45]
	v_pk_add_f32 v[36:37], v[36:37], v[50:51]
	v_pk_add_f32 v[44:45], v[34:35], v[46:47]
	v_pk_add_f32 v[46:47], v[32:33], v[52:53]
	v_mul_f32_e32 v32, v37, v37
	v_mul_f32_e32 v33, v39, v39
	v_mul_f32_e32 v34, v47, v47
	v_fmac_f32_e32 v32, v36, v36
	v_fmac_f32_e32 v33, v38, v38
	v_mul_f32_e32 v35, v45, v45
	v_fmac_f32_e32 v34, v46, v46
	v_add_f32_e32 v32, v32, v33
	v_add_f32_e32 v32, v34, v32
	v_fmac_f32_e32 v35, v44, v44
	v_add_f32_e32 v32, v35, v32
	v_add_f32_e32 v35, v56, v32
	ds_bpermute_b32 v52, v114, v35
	v_lshl_add_u64 v[32:33], s[30:31], 0, v[54:55]
	v_lshl_add_u64 v[50:51], v[32:33], 0, v[138:139]
	global_store_dwordx4 v[50:51], v[40:43], off
	v_cvt_pk_bf16_f32 v34, v36, v37
	s_waitcnt lgkmcnt(0)
	v_add_f32_e32 v32, v35, v52
	ds_bpermute_b32 v33, v115, v32
	v_cvt_pk_bf16_f32 v35, v38, v39
	v_cvt_pk_bf16_f32 v36, v46, v47
	v_cvt_pk_bf16_f32 v37, v44, v45
	global_store_dwordx4 v[50:51], v[34:37], off offset:256
	s_and_saveexec_b64 s[52:53], s[38:39]
	s_cbranch_execz .LBB0_1244
	v_lshl_add_u64 v[34:35], v[48:49], 2, s[36:37]
	s_waitcnt lgkmcnt(0)
	v_add_f32_e32 v32, v32, v33
	global_atomic_add_f32 v[34:35], v32, off
.LBB0_1244:
	s_or_b64 exec, exec, s[52:53]
	v_add_u32_e32 v32, 0xa0, v140
	s_waitcnt lgkmcnt(0)
	v_ashrrev_i32_e32 v33, 31, v32
	v_lshlrev_b64 v[38:39], 11, v[32:33]
	v_lshl_add_u64 v[34:35], s[22:23], 0, v[38:39]
	v_lshl_add_u64 v[40:41], v[34:35], 0, v[138:139]
	s_nop 1
	v_mov_b64_e32 v[34:35], v[218:219]
	v_mov_b64_e32 v[36:37], v[220:221]
	v_lshlrev_b32_e32 v42, 16, v34
	v_and_b32_e32 v43, 0xffff0000, v34
	v_lshlrev_b32_e32 v34, 16, v35
	v_and_b32_e32 v35, 0xffff0000, v35
	v_lshlrev_b32_e32 v44, 16, v36
	v_and_b32_e32 v45, 0xffff0000, v36
	v_lshlrev_b32_e32 v36, 16, v37
	v_and_b32_e32 v37, 0xffff0000, v37
	v_pk_add_f32 v[34:35], v[30:31], v[34:35]
	v_pk_add_f32 v[42:43], v[28:29], v[42:43]
	v_pk_add_f32 v[36:37], v[26:27], v[36:37]
	v_pk_add_f32 v[44:45], v[24:25], v[44:45]
	v_cvt_pk_bf16_f32 v24, v42, v43
	v_cvt_pk_bf16_f32 v25, v34, v35
	v_mul_f32_e32 v35, v35, v35
	v_cvt_pk_bf16_f32 v26, v44, v45
	v_cvt_pk_bf16_f32 v27, v36, v37
	s_nop 1
	v_mov_b64_e32 v[28:29], v[222:223]
	v_mov_b64_e32 v[30:31], v[224:225]
	v_mul_f32_e32 v40, v43, v43
	v_mul_f32_e32 v41, v45, v45
	v_fmac_f32_e32 v40, v42, v42
	v_fmac_f32_e32 v35, v34, v34
	v_mul_f32_e32 v37, v37, v37
	v_fmac_f32_e32 v41, v44, v44
	v_add_f32_e32 v34, v40, v35
	v_fmac_f32_e32 v37, v36, v36
	v_add_f32_e32 v34, v41, v34
	v_add_f32_e32 v40, v37, v34
	v_lshlrev_b32_e32 v34, 16, v28
	v_and_b32_e32 v35, 0xffff0000, v28
	v_lshlrev_b32_e32 v28, 16, v29
	v_and_b32_e32 v29, 0xffff0000, v29
	v_lshlrev_b32_e32 v36, 16, v30
	v_and_b32_e32 v37, 0xffff0000, v30
	v_lshlrev_b32_e32 v30, 16, v31
	v_and_b32_e32 v31, 0xffff0000, v31
	v_pk_add_f32 v[22:23], v[22:23], v[28:29]
	v_pk_add_f32 v[20:21], v[20:21], v[34:35]
	v_pk_add_f32 v[28:29], v[18:19], v[30:31]
	v_pk_add_f32 v[30:31], v[16:17], v[36:37]
	v_mul_f32_e32 v16, v21, v21
	v_mul_f32_e32 v17, v23, v23
	v_mul_f32_e32 v18, v31, v31
	v_fmac_f32_e32 v16, v20, v20
	v_fmac_f32_e32 v17, v22, v22
	v_mul_f32_e32 v19, v29, v29
	v_fmac_f32_e32 v18, v30, v30
	v_add_f32_e32 v16, v16, v17
	v_add_f32_e32 v16, v18, v16
	v_fmac_f32_e32 v19, v28, v28
	v_add_f32_e32 v16, v19, v16
	v_add_f32_e32 v19, v40, v16
	ds_bpermute_b32 v36, v114, v19
	v_lshl_add_u64 v[16:17], s[30:31], 0, v[38:39]
	v_lshl_add_u64 v[34:35], v[16:17], 0, v[138:139]
	global_store_dwordx4 v[34:35], v[24:27], off
	v_cvt_pk_bf16_f32 v18, v20, v21
	s_waitcnt lgkmcnt(0)
	v_add_f32_e32 v16, v19, v36
	ds_bpermute_b32 v17, v115, v16
	v_cvt_pk_bf16_f32 v19, v22, v23
	v_cvt_pk_bf16_f32 v20, v30, v31
	v_cvt_pk_bf16_f32 v21, v28, v29
	global_store_dwordx4 v[34:35], v[18:21], off offset:256
	s_and_saveexec_b64 s[52:53], s[38:39]
	s_cbranch_execz .LBB0_1246
	v_lshl_add_u64 v[18:19], v[32:33], 2, s[36:37]
	s_waitcnt lgkmcnt(0)
	v_add_f32_e32 v16, v16, v17
	global_atomic_add_f32 v[18:19], v16, off
.LBB0_1246:
	s_or_b64 exec, exec, s[52:53]
	v_add_u32_e32 v16, 0xb0, v140
	s_waitcnt lgkmcnt(0)
	v_ashrrev_i32_e32 v17, 31, v16
	v_lshlrev_b64 v[22:23], 11, v[16:17]
	v_lshl_add_u64 v[18:19], s[22:23], 0, v[22:23]
	v_lshl_add_u64 v[24:25], v[18:19], 0, v[138:139]
	s_nop 1
	v_mov_b64_e32 v[18:19], v[226:227]
	v_mov_b64_e32 v[20:21], v[228:229]
	v_lshlrev_b32_e32 v26, 16, v18
	v_and_b32_e32 v27, 0xffff0000, v18
	v_lshlrev_b32_e32 v18, 16, v19
	v_and_b32_e32 v19, 0xffff0000, v19
	v_lshlrev_b32_e32 v28, 16, v20
	v_and_b32_e32 v29, 0xffff0000, v20
	v_lshlrev_b32_e32 v20, 16, v21
	v_and_b32_e32 v21, 0xffff0000, v21
	v_pk_add_f32 v[18:19], v[14:15], v[18:19]
	v_pk_add_f32 v[26:27], v[12:13], v[26:27]
	v_pk_add_f32 v[20:21], v[10:11], v[20:21]
	v_pk_add_f32 v[28:29], v[8:9], v[28:29]
	v_cvt_pk_bf16_f32 v8, v26, v27
	v_cvt_pk_bf16_f32 v9, v18, v19
	v_mul_f32_e32 v19, v19, v19
	v_cvt_pk_bf16_f32 v10, v28, v29
	v_cvt_pk_bf16_f32 v11, v20, v21
	s_nop 1
	v_mov_b64_e32 v[12:13], v[230:231]
	v_mov_b64_e32 v[14:15], v[232:233]
	v_mul_f32_e32 v24, v27, v27
	v_mul_f32_e32 v25, v29, v29
	v_fmac_f32_e32 v24, v26, v26
	v_fmac_f32_e32 v19, v18, v18
	v_mul_f32_e32 v21, v21, v21
	v_fmac_f32_e32 v25, v28, v28
	v_add_f32_e32 v18, v24, v19
	v_fmac_f32_e32 v21, v20, v20
	v_add_f32_e32 v18, v25, v18
	v_add_f32_e32 v24, v21, v18
	v_lshlrev_b32_e32 v18, 16, v12
	v_and_b32_e32 v19, 0xffff0000, v12
	v_lshlrev_b32_e32 v12, 16, v13
	v_and_b32_e32 v13, 0xffff0000, v13
	v_lshlrev_b32_e32 v20, 16, v14
	v_and_b32_e32 v21, 0xffff0000, v14
	v_lshlrev_b32_e32 v14, 16, v15
	v_and_b32_e32 v15, 0xffff0000, v15
	v_pk_add_f32 v[6:7], v[6:7], v[12:13]
	v_pk_add_f32 v[4:5], v[4:5], v[18:19]
	v_pk_add_f32 v[12:13], v[2:3], v[14:15]
	v_pk_add_f32 v[14:15], v[0:1], v[20:21]
	v_mul_f32_e32 v0, v5, v5
	v_mul_f32_e32 v1, v7, v7
	v_mul_f32_e32 v2, v15, v15
	v_fmac_f32_e32 v0, v4, v4
	v_fmac_f32_e32 v1, v6, v6
	v_mul_f32_e32 v3, v13, v13
	v_fmac_f32_e32 v2, v14, v14
	v_add_f32_e32 v0, v0, v1
	v_add_f32_e32 v0, v2, v0
	v_fmac_f32_e32 v3, v12, v12
	v_add_f32_e32 v0, v3, v0
	v_add_f32_e32 v3, v24, v0
	ds_bpermute_b32 v20, v114, v3
	v_lshl_add_u64 v[0:1], s[30:31], 0, v[22:23]
	v_lshl_add_u64 v[18:19], v[0:1], 0, v[138:139]
	global_store_dwordx4 v[18:19], v[8:11], off
	v_cvt_pk_bf16_f32 v2, v4, v5
	s_waitcnt lgkmcnt(0)
	v_add_f32_e32 v0, v3, v20
	ds_bpermute_b32 v1, v115, v0
	v_cvt_pk_bf16_f32 v3, v6, v7
	v_cvt_pk_bf16_f32 v4, v14, v15
	v_cvt_pk_bf16_f32 v5, v12, v13
	global_store_dwordx4 v[18:19], v[2:5], off offset:256
	s_and_saveexec_b64 s[52:53], s[38:39]
	s_cbranch_execz .LBB0_1248
	v_lshl_add_u64 v[2:3], v[16:17], 2, s[36:37]
	s_waitcnt lgkmcnt(0)
	v_add_f32_e32 v0, v0, v1
	global_atomic_add_f32 v[2:3], v0, off
